# seam after FFN1-down: no L2 write-back when every panel's owners share an XCD (everything that phase wrote is consumed on the same XCD)
# speedup vs baseline: 1.0049x; 1.0049x over previous
; __device__ __forceinline__ unsigned xb_add(unsigned* p, unsigned v) { return __hip_atomic_fetch_add(p, v, __ATOMIC_RELAXED, __HIP_MEMORY_SCOPE_AGENT); }
; __device__ __forceinline__ void xcd_barrier(const XcdBarrier& b) {
;     asm volatile("s_waitcnt vmcnt(0)" ::: "memory");
;     __syncthreads();
;     if (threadIdx.x == 0) {
;         unsigned* bar = b.bar;
;         __builtin_amdgcn_s_waitcnt(0);
;         unsigned nloc = b.st[0], nx = b.st[1];
;         if (nloc == 0u) { xcd_barrier_complete(bar, b.x, nloc, nx); b.st[0] = nloc; b.st[1] = nx; }
;         const unsigned old = xb_add(&bar[XB_XSUB(b.x)], 1u);
.LBB0_392:
	s_cmp_gt_i32 s51, 3
	s_cselect_b64 s[4:5], -1, 0
	s_and_b64 s[6:7], s[10:11], s[4:5]
	s_andn2_b64 vcc, exec, s[6:7]
	s_cbranch_vccnz .LBB0_446
	s_cmp_eq_u64 s[44:45], 0
	s_cbranch_scc1 .Lgb2_drain
	s_mov_b64 s[8:9], exec
	s_mov_b64 exec, s[44:45]
	s_lshl_b32 s10, s33, 8
	s_add_u32 s12, s46, s10
	s_addc_u32 s13, s47, 0
	v_mov_b32_e32 v1, 0x23fc0
	ds_read2_b32 v[2:3], v1 offset1:1
	ds_read_b32 v6, v1 offset:8
	v_mov_b32_e32 v0, 0x10000
	global_load_dword v5, v0, s[12:13] sc1
	s_mov_b64 exec, s[8:9]

; __device__ __forceinline__ unsigned xb_ld(unsigned* p)              { return __hip_atomic_load(p, __ATOMIC_RELAXED, __HIP_MEMORY_SCOPE_AGENT); }
; __device__ __forceinline__ unsigned xb_add(unsigned* p, unsigned v) { return __hip_atomic_fetch_add(p, v, __ATOMIC_RELAXED, __HIP_MEMORY_SCOPE_AGENT); }
; #define XB_SPIN(cond, bar) do { unsigned _sp = 0; while (cond) { __builtin_amdgcn_s_sleep(1); \
;     if ((++_sp & 255u) == 0u) { if (xb_ld(&(bar)[XB_TMO])) break; if (_sp > XB_SPIN_CAP) { atomicAdd(&(bar)[XB_TMO], 1u); break; } } } } while (0)
; __device__ __forceinline__ void xcd_barrier(const XcdBarrier& b) {
;     ...
;         const unsigned old = xb_add(&bar[XB_XSUB(b.x)], 1u);
;         const unsigned gen = old / nloc;
;         if (old + 1u == (gen + 1u) * nloc) {
;             __builtin_amdgcn_fence(__ATOMIC_RELEASE, "agent");
;             asm volatile("s_waitcnt vmcnt(0)" ::: "memory");
;             const unsigned og = xb_add(&bar[XB_TOP], 1u);
;             const unsigned tg = og / nx;
;             if (og + 1u == (tg + 1u) * nx) xb_add(&bar[XB_TOPGEN], 1u);
;             else XB_SPIN(xb_ld(&bar[XB_TOPGEN]) == tg, bar);
;             __builtin_amdgcn_fence(__ATOMIC_ACQUIRE, "agent");
;             xb_add(&bar[XB_XGEN(b.x)], 1u);
.Lgb2_prev_ok:
	v_mov_b32_e32 v4, 0x1400
	v_mov_b32_e32 v1, 1
	global_atomic_add v4, v4, v1, s[12:13] sc0
	s_add_i32 s17, s100, 1
	s_mul_i32 s18, s17, s15
	s_mul_i32 s17, s17, s16
	s_waitcnt vmcnt(0) lgkmcnt(0)
	v_readfirstlane_b32 s14, v4
	s_add_i32 s14, s14, 1
	s_cmp_lg_u32 s14, s18
	s_cbranch_scc1 .Lgb2_wait
	v_readfirstlane_b32 s14, v6
	s_cmp_eq_u32 s14, 1
	s_cbranch_scc1 .Lgb2_nowb
	buffer_wbl2 sc1
	s_waitcnt vmcnt(0)
.Lgb2_nowb:
	global_atomic_add v0, v1, s[46:47]
	global_atomic_add v0, v1, s[46:47] offset:256
	global_atomic_add v0, v1, s[46:47] offset:512
	global_atomic_add v0, v1, s[46:47] offset:768
	global_atomic_add v0, v1, s[46:47] offset:1024
	global_atomic_add v0, v1, s[46:47] offset:1280
	global_atomic_add v0, v1, s[46:47] offset:1536
	global_atomic_add v0, v1, s[46:47] offset:1792
	global_atomic_add v0, v1, s[46:47] offset:2048
	global_atomic_add v0, v1, s[46:47] offset:2304
	global_atomic_add v0, v1, s[46:47] offset:2560
	global_atomic_add v0, v1, s[46:47] offset:2816
	global_atomic_add v0, v1, s[46:47] offset:3072
	global_atomic_add v0, v1, s[46:47] offset:3328
	global_atomic_add v0, v1, s[46:47] offset:3584
	global_atomic_add v0, v1, s[46:47] offset:3840
